# GEMM load segments (GEMM1, GLU, out, down): LDS-DMA pieces addressed as SGPR pair + lane offset (+offset:128, M0 compensated), no per-piece VALU adds or s_nop, setprio flips and duplicate waits droppe
# speedup vs baseline: 1.0042x; 1.0042x over previous
.LBB0_32:
	s_add_u32 s12, s10, 0x100
	s_addc_u32 s13, s11, 0
	s_cmpk_eq_i32 s42, 0x52
	s_cselect_b32 s17, s1, s13
	s_cselect_b32 s16, s0, s12
	s_cselect_b32 s15, s9, s41
	s_cselect_b32 s14, s8, s40
	v_add_u32_e32 v142, 0x10000, v207
	v_add_u32_e32 v158, 0x14000, v207
	ds_read_b128 v[130:133], v142
	ds_read_b128 v[134:137], v142 offset:1024
	ds_read_b128 v[138:141], v142 offset:2048
	ds_read_b128 v[142:145], v142 offset:3072
	ds_read_b128 v[146:149], v158
	ds_read_b128 v[150:153], v158 offset:1024
	ds_read_b128 v[154:157], v158 offset:2048
	ds_read_b128 v[158:161], v158 offset:3072
	ds_read_b128 v[162:165], v208
	ds_read_b128 v[166:169], v208 offset:1024
	ds_read_b128 v[170:173], v208 offset:2048
	ds_read_b128 v[184:187], v208 offset:3072
	ds_read_b128 v[188:191], v208 offset:4096
	s_add_i32 m0, s23, 0xc000
	ds_read_b128 v[192:195], v208 offset:5120
	global_load_lds_dwordx4 v180, s[10:11]
	s_add_i32 m0, s23, 0xe000
	ds_read_b128 v[196:199], v208 offset:6144
	global_load_lds_dwordx4 v182, s[10:11]
	ds_read_b128 v[200:203], v208 offset:7168
	s_waitcnt vmcnt(8)
	s_waitcnt lgkmcnt(0)
	s_barrier
	v_mfma_f32_16x16x32_bf16 v[126:129], v[130:133], v[162:165], v[126:129]
	v_mfma_f32_16x16x32_bf16 v[94:97], v[138:141], v[162:165], v[94:97]
	v_mfma_f32_16x16x32_bf16 v[122:125], v[130:133], v[170:173], v[122:125]
	v_mfma_f32_16x16x32_bf16 v[90:93], v[138:141], v[170:173], v[90:93]
	v_mfma_f32_16x16x32_bf16 v[118:121], v[130:133], v[188:191], v[118:121]
	v_mfma_f32_16x16x32_bf16 v[86:89], v[138:141], v[188:191], v[86:89]
	v_mfma_f32_16x16x32_bf16 v[114:117], v[130:133], v[196:199], v[114:117]
	v_mfma_f32_16x16x32_bf16 v[82:85], v[138:141], v[196:199], v[82:85]
	v_mfma_f32_16x16x32_bf16 v[126:129], v[134:137], v[166:169], v[126:129]
	v_mfma_f32_16x16x32_bf16 v[94:97], v[142:145], v[166:169], v[94:97]
	v_mfma_f32_16x16x32_bf16 v[122:125], v[134:137], v[184:187], v[122:125]
	v_mfma_f32_16x16x32_bf16 v[90:93], v[142:145], v[184:187], v[90:93]
	v_mfma_f32_16x16x32_bf16 v[118:121], v[134:137], v[192:195], v[118:121]
	v_mfma_f32_16x16x32_bf16 v[86:89], v[142:145], v[192:195], v[86:89]
	v_mfma_f32_16x16x32_bf16 v[114:117], v[134:137], v[200:203], v[114:117]
	v_mfma_f32_16x16x32_bf16 v[82:85], v[142:145], v[200:203], v[82:85]
	v_mfma_f32_16x16x32_bf16 v[66:69], v[146:149], v[162:165], v[66:69]
	v_mfma_f32_16x16x32_bf16 v[42:45], v[154:157], v[162:165], v[42:45]
	v_mfma_f32_16x16x32_bf16 v[58:61], v[146:149], v[170:173], v[58:61]
	v_mfma_f32_16x16x32_bf16 v[30:33], v[154:157], v[170:173], v[30:33]
	v_mfma_f32_16x16x32_bf16 v[54:57], v[146:149], v[188:191], v[54:57]
	v_mfma_f32_16x16x32_bf16 v[22:25], v[154:157], v[188:191], v[22:25]
	v_mfma_f32_16x16x32_bf16 v[50:53], v[146:149], v[196:199], v[50:53]
	v_mfma_f32_16x16x32_bf16 v[18:21], v[154:157], v[196:199], v[18:21]
	v_mfma_f32_16x16x32_bf16 v[66:69], v[150:153], v[166:169], v[66:69]
	v_mfma_f32_16x16x32_bf16 v[42:45], v[158:161], v[166:169], v[42:45]
	v_mfma_f32_16x16x32_bf16 v[58:61], v[150:153], v[184:187], v[58:61]
	v_mfma_f32_16x16x32_bf16 v[30:33], v[158:161], v[184:187], v[30:33]
	v_mfma_f32_16x16x32_bf16 v[54:57], v[150:153], v[192:195], v[54:57]
	v_mfma_f32_16x16x32_bf16 v[22:25], v[158:161], v[192:195], v[22:25]
	v_mfma_f32_16x16x32_bf16 v[50:53], v[150:153], v[200:203], v[50:53]
	v_mfma_f32_16x16x32_bf16 v[18:21], v[158:161], v[200:203], v[18:21]
	s_barrier
	ds_read_b128 v[162:165], v208 offset:16384
	s_add_i32 m0, s22, 0x10000
	ds_read_b128 v[166:169], v208 offset:17408
	global_load_lds_dwordx4 v178, s[14:15]
	s_add_i32 m0, s22, 0x12000
	s_add_u32 s10, s14, 0x158000
	s_addc_u32 s11, s15, 0
	ds_read_b128 v[170:173], v208 offset:18432
	global_load_lds_dwordx4 v176, s[14:15]
	s_add_i32 m0, s22, 0x14000
	ds_read_b128 v[184:187], v208 offset:19456
	global_load_lds_dwordx4 v178, s[10:11]
	s_add_i32 m0, s22, 0x16000
	ds_read_b128 v[188:191], v208 offset:20480
	global_load_lds_dwordx4 v176, s[10:11]
	s_mov_b32 m0, s23
	ds_read_b128 v[192:195], v208 offset:21504
	global_load_lds_dwordx4 v178, s[16:17]
	s_mov_b32 m0, s24
	ds_read_b128 v[196:199], v208 offset:22528
	global_load_lds_dwordx4 v176, s[16:17]
	ds_read_b128 v[200:203], v208 offset:23552
	s_waitcnt vmcnt(8)
	s_waitcnt lgkmcnt(0)
	s_barrier
	v_mfma_f32_16x16x32_bf16 v[110:113], v[130:133], v[162:165], v[110:113]
	v_mfma_f32_16x16x32_bf16 v[78:81], v[138:141], v[162:165], v[78:81]
	v_mfma_f32_16x16x32_bf16 v[106:109], v[130:133], v[170:173], v[106:109]
	v_mfma_f32_16x16x32_bf16 v[74:77], v[138:141], v[170:173], v[74:77]
	v_mfma_f32_16x16x32_bf16 v[102:105], v[130:133], v[188:191], v[102:105]
	v_mfma_f32_16x16x32_bf16 v[70:73], v[138:141], v[188:191], v[70:73]
	v_mfma_f32_16x16x32_bf16 v[98:101], v[130:133], v[196:199], v[98:101]
	v_mfma_f32_16x16x32_bf16 v[62:65], v[138:141], v[196:199], v[62:65]
	v_mfma_f32_16x16x32_bf16 v[110:113], v[134:137], v[166:169], v[110:113]
	v_mfma_f32_16x16x32_bf16 v[78:81], v[142:145], v[166:169], v[78:81]
	v_mfma_f32_16x16x32_bf16 v[106:109], v[134:137], v[184:187], v[106:109]
	v_mfma_f32_16x16x32_bf16 v[74:77], v[142:145], v[184:187], v[74:77]
	v_mfma_f32_16x16x32_bf16 v[102:105], v[134:137], v[192:195], v[102:105]
	v_mfma_f32_16x16x32_bf16 v[70:73], v[142:145], v[192:195], v[70:73]
	v_mfma_f32_16x16x32_bf16 v[98:101], v[134:137], v[200:203], v[98:101]
	v_mfma_f32_16x16x32_bf16 v[62:65], v[142:145], v[200:203], v[62:65]
	v_mfma_f32_16x16x32_bf16 v[46:49], v[146:149], v[162:165], v[46:49]
	v_mfma_f32_16x16x32_bf16 v[12:15], v[154:157], v[162:165], v[12:15]
	v_mfma_f32_16x16x32_bf16 v[38:41], v[146:149], v[170:173], v[38:41]
	v_mfma_f32_16x16x32_bf16 v[8:11], v[154:157], v[170:173], v[8:11]
	v_mfma_f32_16x16x32_bf16 v[34:37], v[146:149], v[188:191], v[34:37]
	v_mfma_f32_16x16x32_bf16 v[4:7], v[154:157], v[188:191], v[4:7]
	v_mfma_f32_16x16x32_bf16 v[26:29], v[146:149], v[196:199], v[26:29]
	v_mfma_f32_16x16x32_bf16 v[0:3], v[154:157], v[196:199], v[0:3]
	v_mfma_f32_16x16x32_bf16 v[46:49], v[150:153], v[166:169], v[46:49]
	v_mfma_f32_16x16x32_bf16 v[12:15], v[158:161], v[166:169], v[12:15]
	v_mfma_f32_16x16x32_bf16 v[38:41], v[150:153], v[184:187], v[38:41]
	v_mfma_f32_16x16x32_bf16 v[8:11], v[158:161], v[184:187], v[8:11]
	v_mfma_f32_16x16x32_bf16 v[34:37], v[150:153], v[192:195], v[34:37]
	v_mfma_f32_16x16x32_bf16 v[4:7], v[158:161], v[192:195], v[4:7]
	v_mfma_f32_16x16x32_bf16 v[26:29], v[150:153], v[200:203], v[26:29]
	v_mfma_f32_16x16x32_bf16 v[0:3], v[158:161], v[200:203], v[0:3]
	s_barrier
	s_add_u32 s100, s16, 0x158000
	s_addc_u32 s101, s17, 0
	v_add_u32_e32 v142, 0x18000, v207
	v_add_u32_e32 v158, 0x1c000, v207
	ds_read_b128 v[130:133], v142
	ds_read_b128 v[134:137], v142 offset:1024
	ds_read_b128 v[138:141], v142 offset:2048
	ds_read_b128 v[142:145], v142 offset:3072
	ds_read_b128 v[146:149], v158
	ds_read_b128 v[150:153], v158 offset:1024
	ds_read_b128 v[154:157], v158 offset:2048
	ds_read_b128 v[158:161], v158 offset:3072
	ds_read_b128 v[162:165], v208 offset:32768
	ds_read_b128 v[166:169], v208 offset:33792
	ds_read_b128 v[170:173], v208 offset:34816
	ds_read_b128 v[184:187], v208 offset:35840
	ds_read_b128 v[188:191], v208 offset:36864
	s_mov_b32 m0, s25
	ds_read_b128 v[192:195], v208 offset:37888
	global_load_lds_dwordx4 v178, s[100:101]
	s_mov_b32 m0, s26
	ds_read_b128 v[196:199], v208 offset:38912
	global_load_lds_dwordx4 v176, s[100:101]
	ds_read_b128 v[200:203], v208 offset:39936
	s_waitcnt vmcnt(8)
	s_waitcnt lgkmcnt(0)
	s_barrier
	v_mfma_f32_16x16x32_bf16 v[126:129], v[130:133], v[162:165], v[126:129]
	v_mfma_f32_16x16x32_bf16 v[94:97], v[138:141], v[162:165], v[94:97]
	v_mfma_f32_16x16x32_bf16 v[122:125], v[130:133], v[170:173], v[122:125]
	v_mfma_f32_16x16x32_bf16 v[90:93], v[138:141], v[170:173], v[90:93]
	v_mfma_f32_16x16x32_bf16 v[118:121], v[130:133], v[188:191], v[118:121]
	v_mfma_f32_16x16x32_bf16 v[86:89], v[138:141], v[188:191], v[86:89]
	v_mfma_f32_16x16x32_bf16 v[114:117], v[130:133], v[196:199], v[114:117]
	v_mfma_f32_16x16x32_bf16 v[82:85], v[138:141], v[196:199], v[82:85]
	v_mfma_f32_16x16x32_bf16 v[126:129], v[134:137], v[166:169], v[126:129]
	v_mfma_f32_16x16x32_bf16 v[94:97], v[142:145], v[166:169], v[94:97]
	v_mfma_f32_16x16x32_bf16 v[122:125], v[134:137], v[184:187], v[122:125]
	v_mfma_f32_16x16x32_bf16 v[90:93], v[142:145], v[184:187], v[90:93]
	v_mfma_f32_16x16x32_bf16 v[118:121], v[134:137], v[192:195], v[118:121]
	v_mfma_f32_16x16x32_bf16 v[86:89], v[142:145], v[192:195], v[86:89]
	v_mfma_f32_16x16x32_bf16 v[114:117], v[134:137], v[200:203], v[114:117]
	v_mfma_f32_16x16x32_bf16 v[82:85], v[142:145], v[200:203], v[82:85]
	v_mfma_f32_16x16x32_bf16 v[66:69], v[146:149], v[162:165], v[66:69]
	v_mfma_f32_16x16x32_bf16 v[42:45], v[154:157], v[162:165], v[42:45]
	v_mfma_f32_16x16x32_bf16 v[58:61], v[146:149], v[170:173], v[58:61]
	v_mfma_f32_16x16x32_bf16 v[30:33], v[154:157], v[170:173], v[30:33]
	v_mfma_f32_16x16x32_bf16 v[54:57], v[146:149], v[188:191], v[54:57]
	v_mfma_f32_16x16x32_bf16 v[22:25], v[154:157], v[188:191], v[22:25]
	v_mfma_f32_16x16x32_bf16 v[50:53], v[146:149], v[196:199], v[50:53]
	v_mfma_f32_16x16x32_bf16 v[18:21], v[154:157], v[196:199], v[18:21]
	v_mfma_f32_16x16x32_bf16 v[66:69], v[150:153], v[166:169], v[66:69]
	v_mfma_f32_16x16x32_bf16 v[42:45], v[158:161], v[166:169], v[42:45]
	v_mfma_f32_16x16x32_bf16 v[58:61], v[150:153], v[184:187], v[58:61]
	v_mfma_f32_16x16x32_bf16 v[30:33], v[158:161], v[184:187], v[30:33]
	v_mfma_f32_16x16x32_bf16 v[54:57], v[150:153], v[192:195], v[54:57]
	v_mfma_f32_16x16x32_bf16 v[22:25], v[158:161], v[192:195], v[22:25]
	v_mfma_f32_16x16x32_bf16 v[50:53], v[150:153], v[200:203], v[50:53]
	v_mfma_f32_16x16x32_bf16 v[18:21], v[158:161], v[200:203], v[18:21]
	s_barrier
	ds_read_b128 v[162:165], v208 offset:49152
	s_add_i32 m0, s22, 0x17f80
	ds_read_b128 v[166:169], v208 offset:50176
	global_load_lds_dwordx4 v178, s[14:15] offset:128
	s_add_i32 m0, s22, 0x19f80
	ds_read_b128 v[170:173], v208 offset:51200
	global_load_lds_dwordx4 v176, s[14:15] offset:128
	s_add_i32 m0, s22, 0x1bf80
	ds_read_b128 v[184:187], v208 offset:52224
	global_load_lds_dwordx4 v178, s[10:11] offset:128
	s_add_i32 m0, s22, 0x1df80
	ds_read_b128 v[188:191], v208 offset:53248
	global_load_lds_dwordx4 v176, s[10:11] offset:128
	s_add_i32 m0, s31, 0xffffff80
	ds_read_b128 v[192:195], v208 offset:54272
	global_load_lds_dwordx4 v178, s[16:17] offset:128
	s_add_i32 m0, s34, 0xffffff80
	ds_read_b128 v[196:199], v208 offset:55296
	global_load_lds_dwordx4 v176, s[16:17] offset:128
	ds_read_b128 v[200:203], v208 offset:56320
	s_waitcnt vmcnt(8)
	s_waitcnt lgkmcnt(0)
	s_barrier
	v_mfma_f32_16x16x32_bf16 v[110:113], v[130:133], v[162:165], v[110:113]
	v_mfma_f32_16x16x32_bf16 v[78:81], v[138:141], v[162:165], v[78:81]
	v_mfma_f32_16x16x32_bf16 v[106:109], v[130:133], v[170:173], v[106:109]
	v_mfma_f32_16x16x32_bf16 v[74:77], v[138:141], v[170:173], v[74:77]
	v_mfma_f32_16x16x32_bf16 v[102:105], v[130:133], v[188:191], v[102:105]
	v_mfma_f32_16x16x32_bf16 v[70:73], v[138:141], v[188:191], v[70:73]
	v_mfma_f32_16x16x32_bf16 v[98:101], v[130:133], v[196:199], v[98:101]
	v_mfma_f32_16x16x32_bf16 v[62:65], v[138:141], v[196:199], v[62:65]
	v_mfma_f32_16x16x32_bf16 v[110:113], v[134:137], v[166:169], v[110:113]
	v_mfma_f32_16x16x32_bf16 v[78:81], v[142:145], v[166:169], v[78:81]
	v_mfma_f32_16x16x32_bf16 v[106:109], v[134:137], v[184:187], v[106:109]
	v_mfma_f32_16x16x32_bf16 v[74:77], v[142:145], v[184:187], v[74:77]
	v_mfma_f32_16x16x32_bf16 v[102:105], v[134:137], v[192:195], v[102:105]
	v_mfma_f32_16x16x32_bf16 v[70:73], v[142:145], v[192:195], v[70:73]
	v_mfma_f32_16x16x32_bf16 v[98:101], v[134:137], v[200:203], v[98:101]
	v_mfma_f32_16x16x32_bf16 v[62:65], v[142:145], v[200:203], v[62:65]
	v_mfma_f32_16x16x32_bf16 v[46:49], v[146:149], v[162:165], v[46:49]
	v_mfma_f32_16x16x32_bf16 v[12:15], v[154:157], v[162:165], v[12:15]
	v_mfma_f32_16x16x32_bf16 v[38:41], v[146:149], v[170:173], v[38:41]
	v_mfma_f32_16x16x32_bf16 v[8:11], v[154:157], v[170:173], v[8:11]
	v_mfma_f32_16x16x32_bf16 v[34:37], v[146:149], v[188:191], v[34:37]
	v_mfma_f32_16x16x32_bf16 v[4:7], v[154:157], v[188:191], v[4:7]
	v_mfma_f32_16x16x32_bf16 v[26:29], v[146:149], v[196:199], v[26:29]
	v_mfma_f32_16x16x32_bf16 v[0:3], v[154:157], v[196:199], v[0:3]
	v_mfma_f32_16x16x32_bf16 v[46:49], v[150:153], v[166:169], v[46:49]
	v_mfma_f32_16x16x32_bf16 v[12:15], v[158:161], v[166:169], v[12:15]
	v_mfma_f32_16x16x32_bf16 v[38:41], v[150:153], v[184:187], v[38:41]
	v_mfma_f32_16x16x32_bf16 v[8:11], v[158:161], v[184:187], v[8:11]
	v_mfma_f32_16x16x32_bf16 v[34:37], v[150:153], v[192:195], v[34:37]
	v_mfma_f32_16x16x32_bf16 v[4:7], v[158:161], v[192:195], v[4:7]
	v_mfma_f32_16x16x32_bf16 v[26:29], v[150:153], v[200:203], v[26:29]
	v_mfma_f32_16x16x32_bf16 v[0:3], v[158:161], v[200:203], v[0:3]
	s_barrier
	s_add_i32 s42, s42, 2
	s_add_u32 s40, s40, 0x100
	s_addc_u32 s41, s41, 0
	s_cmpk_gt_u32 s42, 0x53
	s_mov_b64 s[10:11], s[12:13]
	s_cbranch_scc0 .LBB0_32
	s_and_b64 vcc, exec, s[6:7]
	s_cbranch_vccz .LBB0_35
	s_barrier

.LBB0_108:
	s_add_u32 s16, s14, 0xfff80080
	s_addc_u32 s17, s15, -1
	s_cmp_eq_u32 s44, 28
	s_cselect_b32 s19, s9, s17
	s_cselect_b32 s18, s40, s16
	s_cselect_b32 s17, s7, s43
	s_cselect_b32 s16, s41, s42
	v_add_u32_e32 v142, 0x10000, v207
	v_add_u32_e32 v158, 0x14000, v207
	ds_read_b128 v[130:133], v142
	ds_read_b128 v[134:137], v142 offset:1024
	ds_read_b128 v[138:141], v142 offset:2048
	ds_read_b128 v[142:145], v142 offset:3072
	ds_read_b128 v[146:149], v158
	ds_read_b128 v[150:153], v158 offset:1024
	ds_read_b128 v[154:157], v158 offset:2048
	ds_read_b128 v[158:161], v158 offset:3072
	ds_read_b128 v[162:165], v208
	ds_read_b128 v[166:169], v208 offset:1024
	ds_read_b128 v[184:187], v208 offset:2048
	ds_read_b128 v[188:191], v208 offset:3072
	ds_read_b128 v[192:195], v208 offset:4096
	s_add_i32 m0, s25, 0xc000
	ds_read_b128 v[196:199], v208 offset:5120
	global_load_lds_dwordx4 v180, s[14:15]
	s_add_i32 m0, s25, 0xe000
	ds_read_b128 v[200:203], v208 offset:6144
	global_load_lds_dwordx4 v182, s[14:15]
	ds_read_b128 v[210:213], v208 offset:7168
	s_waitcnt vmcnt(8)
	s_waitcnt lgkmcnt(0)
	s_barrier
	v_mfma_f32_16x16x32_bf16 v[126:129], v[130:133], v[162:165], v[126:129]
	v_mfma_f32_16x16x32_bf16 v[94:97], v[138:141], v[162:165], v[94:97]
	v_mfma_f32_16x16x32_bf16 v[122:125], v[130:133], v[184:187], v[122:125]
	v_mfma_f32_16x16x32_bf16 v[90:93], v[138:141], v[184:187], v[90:93]
	v_mfma_f32_16x16x32_bf16 v[118:121], v[130:133], v[192:195], v[118:121]
	v_mfma_f32_16x16x32_bf16 v[86:89], v[138:141], v[192:195], v[86:89]
	v_mfma_f32_16x16x32_bf16 v[114:117], v[130:133], v[200:203], v[114:117]
	v_mfma_f32_16x16x32_bf16 v[82:85], v[138:141], v[200:203], v[82:85]
	v_mfma_f32_16x16x32_bf16 v[126:129], v[134:137], v[166:169], v[126:129]
	v_mfma_f32_16x16x32_bf16 v[94:97], v[142:145], v[166:169], v[94:97]
	v_mfma_f32_16x16x32_bf16 v[122:125], v[134:137], v[188:191], v[122:125]
	v_mfma_f32_16x16x32_bf16 v[90:93], v[142:145], v[188:191], v[90:93]
	v_mfma_f32_16x16x32_bf16 v[118:121], v[134:137], v[196:199], v[118:121]
	v_mfma_f32_16x16x32_bf16 v[86:89], v[142:145], v[196:199], v[86:89]
	v_mfma_f32_16x16x32_bf16 v[114:117], v[134:137], v[210:213], v[114:117]
	v_mfma_f32_16x16x32_bf16 v[82:85], v[142:145], v[210:213], v[82:85]
	v_mfma_f32_16x16x32_bf16 v[66:69], v[146:149], v[162:165], v[66:69]
	v_mfma_f32_16x16x32_bf16 v[42:45], v[154:157], v[162:165], v[42:45]
	v_mfma_f32_16x16x32_bf16 v[58:61], v[146:149], v[184:187], v[58:61]
	v_mfma_f32_16x16x32_bf16 v[30:33], v[154:157], v[184:187], v[30:33]
	v_mfma_f32_16x16x32_bf16 v[54:57], v[146:149], v[192:195], v[54:57]
	v_mfma_f32_16x16x32_bf16 v[22:25], v[154:157], v[192:195], v[22:25]
	v_mfma_f32_16x16x32_bf16 v[50:53], v[146:149], v[200:203], v[50:53]
	v_mfma_f32_16x16x32_bf16 v[18:21], v[154:157], v[200:203], v[18:21]
	v_mfma_f32_16x16x32_bf16 v[66:69], v[150:153], v[166:169], v[66:69]
	v_mfma_f32_16x16x32_bf16 v[42:45], v[158:161], v[166:169], v[42:45]
	v_mfma_f32_16x16x32_bf16 v[58:61], v[150:153], v[188:191], v[58:61]
	v_mfma_f32_16x16x32_bf16 v[30:33], v[158:161], v[188:191], v[30:33]
	v_mfma_f32_16x16x32_bf16 v[54:57], v[150:153], v[196:199], v[54:57]
	v_mfma_f32_16x16x32_bf16 v[22:25], v[158:161], v[196:199], v[22:25]
	v_mfma_f32_16x16x32_bf16 v[50:53], v[150:153], v[210:213], v[50:53]
	v_mfma_f32_16x16x32_bf16 v[18:21], v[158:161], v[210:213], v[18:21]
	s_barrier
	ds_read_b128 v[162:165], v208 offset:16384
	s_add_i32 m0, s24, 0x10000
	ds_read_b128 v[166:169], v208 offset:17408
	global_load_lds_dwordx4 v178, s[16:17]
	s_add_i32 m0, s24, 0x12000
	s_add_u32 s46, s16, 0x80000
	s_addc_u32 s47, s17, 0
	ds_read_b128 v[184:187], v208 offset:18432
	global_load_lds_dwordx4 v176, s[16:17]
	s_add_i32 m0, s24, 0x14000
	ds_read_b128 v[188:191], v208 offset:19456
	global_load_lds_dwordx4 v178, s[46:47]
	s_add_i32 m0, s24, 0x16000
	ds_read_b128 v[192:195], v208 offset:20480
	global_load_lds_dwordx4 v176, s[46:47]
	s_mov_b32 m0, s25
	ds_read_b128 v[196:199], v208 offset:21504
	global_load_lds_dwordx4 v178, s[18:19]
	s_mov_b32 m0, s26
	ds_read_b128 v[200:203], v208 offset:22528
	global_load_lds_dwordx4 v176, s[18:19]
	ds_read_b128 v[210:213], v208 offset:23552
	s_waitcnt vmcnt(8)
	s_waitcnt lgkmcnt(0)
	s_barrier
	v_mfma_f32_16x16x32_bf16 v[110:113], v[130:133], v[162:165], v[110:113]
	v_mfma_f32_16x16x32_bf16 v[78:81], v[138:141], v[162:165], v[78:81]
	v_mfma_f32_16x16x32_bf16 v[106:109], v[130:133], v[184:187], v[106:109]
	v_mfma_f32_16x16x32_bf16 v[74:77], v[138:141], v[184:187], v[74:77]
	v_mfma_f32_16x16x32_bf16 v[102:105], v[130:133], v[192:195], v[102:105]
	v_mfma_f32_16x16x32_bf16 v[70:73], v[138:141], v[192:195], v[70:73]
	v_mfma_f32_16x16x32_bf16 v[98:101], v[130:133], v[200:203], v[98:101]
	v_mfma_f32_16x16x32_bf16 v[62:65], v[138:141], v[200:203], v[62:65]
	v_mfma_f32_16x16x32_bf16 v[110:113], v[134:137], v[166:169], v[110:113]
	v_mfma_f32_16x16x32_bf16 v[78:81], v[142:145], v[166:169], v[78:81]
	v_mfma_f32_16x16x32_bf16 v[106:109], v[134:137], v[188:191], v[106:109]
	v_mfma_f32_16x16x32_bf16 v[74:77], v[142:145], v[188:191], v[74:77]
	v_mfma_f32_16x16x32_bf16 v[102:105], v[134:137], v[196:199], v[102:105]
	v_mfma_f32_16x16x32_bf16 v[70:73], v[142:145], v[196:199], v[70:73]
	v_mfma_f32_16x16x32_bf16 v[98:101], v[134:137], v[210:213], v[98:101]
	v_mfma_f32_16x16x32_bf16 v[62:65], v[142:145], v[210:213], v[62:65]
	v_mfma_f32_16x16x32_bf16 v[46:49], v[146:149], v[162:165], v[46:49]
	v_mfma_f32_16x16x32_bf16 v[12:15], v[154:157], v[162:165], v[12:15]
	v_mfma_f32_16x16x32_bf16 v[38:41], v[146:149], v[184:187], v[38:41]
	v_mfma_f32_16x16x32_bf16 v[8:11], v[154:157], v[184:187], v[8:11]
	v_mfma_f32_16x16x32_bf16 v[34:37], v[146:149], v[192:195], v[34:37]
	v_mfma_f32_16x16x32_bf16 v[4:7], v[154:157], v[192:195], v[4:7]
	v_mfma_f32_16x16x32_bf16 v[26:29], v[146:149], v[200:203], v[26:29]
	v_mfma_f32_16x16x32_bf16 v[0:3], v[154:157], v[200:203], v[0:3]
	v_mfma_f32_16x16x32_bf16 v[46:49], v[150:153], v[166:169], v[46:49]
	v_mfma_f32_16x16x32_bf16 v[12:15], v[158:161], v[166:169], v[12:15]
	v_mfma_f32_16x16x32_bf16 v[38:41], v[150:153], v[188:191], v[38:41]
	v_mfma_f32_16x16x32_bf16 v[8:11], v[158:161], v[188:191], v[8:11]
	v_mfma_f32_16x16x32_bf16 v[34:37], v[150:153], v[196:199], v[34:37]
	v_mfma_f32_16x16x32_bf16 v[4:7], v[158:161], v[196:199], v[4:7]
	v_mfma_f32_16x16x32_bf16 v[26:29], v[150:153], v[210:213], v[26:29]
	v_mfma_f32_16x16x32_bf16 v[0:3], v[158:161], v[210:213], v[0:3]
	s_barrier
	s_add_u32 s100, s18, 0x80000
	s_addc_u32 s101, s19, 0
	v_add_u32_e32 v142, 0x18000, v207
	v_add_u32_e32 v158, 0x1c000, v207
	ds_read_b128 v[130:133], v142
	ds_read_b128 v[134:137], v142 offset:1024
	ds_read_b128 v[138:141], v142 offset:2048
	ds_read_b128 v[142:145], v142 offset:3072
	ds_read_b128 v[146:149], v158
	ds_read_b128 v[150:153], v158 offset:1024
	ds_read_b128 v[154:157], v158 offset:2048
	ds_read_b128 v[158:161], v158 offset:3072
	ds_read_b128 v[162:165], v208 offset:32768
	ds_read_b128 v[166:169], v208 offset:33792
	ds_read_b128 v[184:187], v208 offset:34816
	ds_read_b128 v[188:191], v208 offset:35840
	ds_read_b128 v[192:195], v208 offset:36864
	s_mov_b32 m0, s27
	ds_read_b128 v[196:199], v208 offset:37888
	global_load_lds_dwordx4 v178, s[100:101]
	s_mov_b32 m0, s28
	ds_read_b128 v[200:203], v208 offset:38912
	global_load_lds_dwordx4 v176, s[100:101]
	ds_read_b128 v[210:213], v208 offset:39936
	s_waitcnt vmcnt(8)
	s_waitcnt lgkmcnt(0)
	s_barrier
	v_mfma_f32_16x16x32_bf16 v[126:129], v[130:133], v[162:165], v[126:129]
	v_mfma_f32_16x16x32_bf16 v[94:97], v[138:141], v[162:165], v[94:97]
	v_mfma_f32_16x16x32_bf16 v[122:125], v[130:133], v[184:187], v[122:125]
	v_mfma_f32_16x16x32_bf16 v[90:93], v[138:141], v[184:187], v[90:93]
	v_mfma_f32_16x16x32_bf16 v[118:121], v[130:133], v[192:195], v[118:121]
	v_mfma_f32_16x16x32_bf16 v[86:89], v[138:141], v[192:195], v[86:89]
	v_mfma_f32_16x16x32_bf16 v[114:117], v[130:133], v[200:203], v[114:117]
	v_mfma_f32_16x16x32_bf16 v[82:85], v[138:141], v[200:203], v[82:85]
	v_mfma_f32_16x16x32_bf16 v[126:129], v[134:137], v[166:169], v[126:129]
	v_mfma_f32_16x16x32_bf16 v[94:97], v[142:145], v[166:169], v[94:97]
	v_mfma_f32_16x16x32_bf16 v[122:125], v[134:137], v[188:191], v[122:125]
	v_mfma_f32_16x16x32_bf16 v[90:93], v[142:145], v[188:191], v[90:93]
	v_mfma_f32_16x16x32_bf16 v[118:121], v[134:137], v[196:199], v[118:121]
	v_mfma_f32_16x16x32_bf16 v[86:89], v[142:145], v[196:199], v[86:89]
	v_mfma_f32_16x16x32_bf16 v[114:117], v[134:137], v[210:213], v[114:117]
	v_mfma_f32_16x16x32_bf16 v[82:85], v[142:145], v[210:213], v[82:85]
	v_mfma_f32_16x16x32_bf16 v[66:69], v[146:149], v[162:165], v[66:69]
	v_mfma_f32_16x16x32_bf16 v[42:45], v[154:157], v[162:165], v[42:45]
	v_mfma_f32_16x16x32_bf16 v[58:61], v[146:149], v[184:187], v[58:61]
	v_mfma_f32_16x16x32_bf16 v[30:33], v[154:157], v[184:187], v[30:33]
	v_mfma_f32_16x16x32_bf16 v[54:57], v[146:149], v[192:195], v[54:57]
	v_mfma_f32_16x16x32_bf16 v[22:25], v[154:157], v[192:195], v[22:25]
	v_mfma_f32_16x16x32_bf16 v[50:53], v[146:149], v[200:203], v[50:53]
	v_mfma_f32_16x16x32_bf16 v[18:21], v[154:157], v[200:203], v[18:21]
	v_mfma_f32_16x16x32_bf16 v[66:69], v[150:153], v[166:169], v[66:69]
	v_mfma_f32_16x16x32_bf16 v[42:45], v[158:161], v[166:169], v[42:45]
	v_mfma_f32_16x16x32_bf16 v[58:61], v[150:153], v[188:191], v[58:61]
	v_mfma_f32_16x16x32_bf16 v[30:33], v[158:161], v[188:191], v[30:33]
	v_mfma_f32_16x16x32_bf16 v[54:57], v[150:153], v[196:199], v[54:57]
	v_mfma_f32_16x16x32_bf16 v[22:25], v[158:161], v[196:199], v[22:25]
	v_mfma_f32_16x16x32_bf16 v[50:53], v[150:153], v[210:213], v[50:53]
	v_mfma_f32_16x16x32_bf16 v[18:21], v[158:161], v[210:213], v[18:21]
	s_barrier
	ds_read_b128 v[162:165], v208 offset:49152
	s_add_i32 m0, s24, 0x17f80
	ds_read_b128 v[166:169], v208 offset:50176
	global_load_lds_dwordx4 v178, s[16:17] offset:128
	s_add_i32 m0, s24, 0x19f80
	ds_read_b128 v[184:187], v208 offset:51200
	global_load_lds_dwordx4 v176, s[16:17] offset:128
	s_add_i32 m0, s24, 0x1bf80
	ds_read_b128 v[188:191], v208 offset:52224
	global_load_lds_dwordx4 v178, s[46:47] offset:128
	s_add_i32 m0, s24, 0x1df80
	ds_read_b128 v[192:195], v208 offset:53248
	global_load_lds_dwordx4 v176, s[46:47] offset:128
	s_add_i32 m0, s35, 0xffffff80
	ds_read_b128 v[196:199], v208 offset:54272
	global_load_lds_dwordx4 v178, s[18:19] offset:128
	s_add_i32 m0, s36, 0xffffff80
	ds_read_b128 v[200:203], v208 offset:55296
	global_load_lds_dwordx4 v176, s[18:19] offset:128
	ds_read_b128 v[210:213], v208 offset:56320
	s_waitcnt vmcnt(8)
	s_waitcnt lgkmcnt(0)
	s_barrier
	v_mfma_f32_16x16x32_bf16 v[110:113], v[130:133], v[162:165], v[110:113]
	v_mfma_f32_16x16x32_bf16 v[78:81], v[138:141], v[162:165], v[78:81]
	v_mfma_f32_16x16x32_bf16 v[106:109], v[130:133], v[184:187], v[106:109]
	v_mfma_f32_16x16x32_bf16 v[74:77], v[138:141], v[184:187], v[74:77]
	v_mfma_f32_16x16x32_bf16 v[102:105], v[130:133], v[192:195], v[102:105]
	v_mfma_f32_16x16x32_bf16 v[70:73], v[138:141], v[192:195], v[70:73]
	v_mfma_f32_16x16x32_bf16 v[98:101], v[130:133], v[200:203], v[98:101]
	v_mfma_f32_16x16x32_bf16 v[62:65], v[138:141], v[200:203], v[62:65]
	v_mfma_f32_16x16x32_bf16 v[110:113], v[134:137], v[166:169], v[110:113]
	v_mfma_f32_16x16x32_bf16 v[78:81], v[142:145], v[166:169], v[78:81]
	v_mfma_f32_16x16x32_bf16 v[106:109], v[134:137], v[188:191], v[106:109]
	v_mfma_f32_16x16x32_bf16 v[74:77], v[142:145], v[188:191], v[74:77]
	v_mfma_f32_16x16x32_bf16 v[102:105], v[134:137], v[196:199], v[102:105]
	v_mfma_f32_16x16x32_bf16 v[70:73], v[142:145], v[196:199], v[70:73]
	v_mfma_f32_16x16x32_bf16 v[98:101], v[134:137], v[210:213], v[98:101]
	v_mfma_f32_16x16x32_bf16 v[62:65], v[142:145], v[210:213], v[62:65]
	v_mfma_f32_16x16x32_bf16 v[46:49], v[146:149], v[162:165], v[46:49]
	v_mfma_f32_16x16x32_bf16 v[12:15], v[154:157], v[162:165], v[12:15]
	v_mfma_f32_16x16x32_bf16 v[38:41], v[146:149], v[184:187], v[38:41]
	v_mfma_f32_16x16x32_bf16 v[8:11], v[154:157], v[184:187], v[8:11]
	v_mfma_f32_16x16x32_bf16 v[34:37], v[146:149], v[192:195], v[34:37]
	v_mfma_f32_16x16x32_bf16 v[4:7], v[154:157], v[192:195], v[4:7]
	v_mfma_f32_16x16x32_bf16 v[26:29], v[146:149], v[200:203], v[26:29]
	v_mfma_f32_16x16x32_bf16 v[0:3], v[154:157], v[200:203], v[0:3]
	v_mfma_f32_16x16x32_bf16 v[46:49], v[150:153], v[166:169], v[46:49]
	v_mfma_f32_16x16x32_bf16 v[12:15], v[158:161], v[166:169], v[12:15]
	v_mfma_f32_16x16x32_bf16 v[38:41], v[150:153], v[188:191], v[38:41]
	v_mfma_f32_16x16x32_bf16 v[8:11], v[158:161], v[188:191], v[8:11]
	v_mfma_f32_16x16x32_bf16 v[34:37], v[150:153], v[196:199], v[34:37]
	v_mfma_f32_16x16x32_bf16 v[4:7], v[158:161], v[196:199], v[4:7]
	v_mfma_f32_16x16x32_bf16 v[26:29], v[150:153], v[210:213], v[26:29]
	v_mfma_f32_16x16x32_bf16 v[0:3], v[158:161], v[210:213], v[0:3]
	s_barrier
	s_add_i32 s44, s44, 2
	s_add_u32 s14, s14, 0x100
	s_addc_u32 s15, s15, 0
	s_add_u32 s42, s42, 0x100
	s_addc_u32 s43, s43, 0
	s_cmp_gt_u32 s44, 29
	s_cbranch_scc0 .LBB0_108
	s_and_b64 vcc, exec, s[2:3]
	s_movk_i32 s44, 0x1000
	s_cbranch_vccz .LBB0_111
	s_barrier

.LBB0_552:
	s_add_u32 s8, s6, 0xfffe0080
	s_addc_u32 s9, s7, -1
	s_cmp_eq_u32 s46, 4
	s_cselect_b32 s25, s19, s9
	s_cselect_b32 s24, s42, s8
	s_cselect_b32 s9, s17, s45
	s_cselect_b32 s8, s43, s44
	v_add_u32_e32 v86, 0x10000, v184
	v_add_u32_e32 v168, 0x14000, v184
	ds_read_b128 v[58:61], v86
	ds_read_b128 v[70:73], v86 offset:1024
	ds_read_b128 v[74:77], v86 offset:2048
	ds_read_b128 v[86:89], v86 offset:3072
	ds_read_b128 v[122:125], v168
	ds_read_b128 v[126:129], v168 offset:1024
	ds_read_b128 v[154:157], v168 offset:2048
	ds_read_b128 v[176:179], v168 offset:3072
	ds_read_b128 v[186:189], v185
	ds_read_b128 v[190:193], v185 offset:1024
	ds_read_b128 v[194:197], v185 offset:2048
	ds_read_b128 v[198:201], v185 offset:3072
	ds_read_b128 v[202:205], v185 offset:4096
	s_add_i32 m0, s31, 0xc000
	ds_read_b128 v[206:209], v185 offset:5120
	global_load_lds_dwordx4 v164, s[6:7]
	s_add_i32 m0, s31, 0xe000
	ds_read_b128 v[210:213], v185 offset:6144
	global_load_lds_dwordx4 v166, s[6:7]
	ds_read_b128 v[230:233], v185 offset:7168
	s_waitcnt vmcnt(8)
	s_waitcnt lgkmcnt(0)
	s_barrier
	v_mfma_f32_16x16x32_bf16 v[150:153], v[58:61], v[186:189], v[150:153]
	v_mfma_f32_16x16x32_bf16 v[146:149], v[74:77], v[186:189], v[146:149]
	v_mfma_f32_16x16x32_bf16 v[142:145], v[58:61], v[194:197], v[142:145]
	v_mfma_f32_16x16x32_bf16 v[138:141], v[74:77], v[194:197], v[138:141]
	v_mfma_f32_16x16x32_bf16 v[134:137], v[58:61], v[202:205], v[134:137]
	v_mfma_f32_16x16x32_bf16 v[130:133], v[74:77], v[202:205], v[130:133]
	v_mfma_f32_16x16x32_bf16 v[118:121], v[58:61], v[210:213], v[118:121]
	v_mfma_f32_16x16x32_bf16 v[114:117], v[74:77], v[210:213], v[114:117]
	v_mfma_f32_16x16x32_bf16 v[150:153], v[70:73], v[190:193], v[150:153]
	v_mfma_f32_16x16x32_bf16 v[146:149], v[86:89], v[190:193], v[146:149]
	v_mfma_f32_16x16x32_bf16 v[142:145], v[70:73], v[198:201], v[142:145]
	v_mfma_f32_16x16x32_bf16 v[138:141], v[86:89], v[198:201], v[138:141]
	v_mfma_f32_16x16x32_bf16 v[134:137], v[70:73], v[206:209], v[134:137]
	v_mfma_f32_16x16x32_bf16 v[130:133], v[86:89], v[206:209], v[130:133]
	v_mfma_f32_16x16x32_bf16 v[118:121], v[70:73], v[230:233], v[118:121]
	v_mfma_f32_16x16x32_bf16 v[114:117], v[86:89], v[230:233], v[114:117]
	v_mfma_f32_16x16x32_bf16 v[66:69], v[122:125], v[186:189], v[66:69]
	v_mfma_f32_16x16x32_bf16 v[62:65], v[154:157], v[186:189], v[62:65]
	v_mfma_f32_16x16x32_bf16 v[54:57], v[122:125], v[194:197], v[54:57]
	v_mfma_f32_16x16x32_bf16 v[50:53], v[154:157], v[194:197], v[50:53]
	v_mfma_f32_16x16x32_bf16 v[46:49], v[122:125], v[202:205], v[46:49]
	v_mfma_f32_16x16x32_bf16 v[42:45], v[154:157], v[202:205], v[42:45]
	v_mfma_f32_16x16x32_bf16 v[38:41], v[122:125], v[210:213], v[38:41]
	v_mfma_f32_16x16x32_bf16 v[34:37], v[154:157], v[210:213], v[34:37]
	v_mfma_f32_16x16x32_bf16 v[66:69], v[126:129], v[190:193], v[66:69]
	v_mfma_f32_16x16x32_bf16 v[62:65], v[176:179], v[190:193], v[62:65]
	v_mfma_f32_16x16x32_bf16 v[54:57], v[126:129], v[198:201], v[54:57]
	v_mfma_f32_16x16x32_bf16 v[50:53], v[176:179], v[198:201], v[50:53]
	v_mfma_f32_16x16x32_bf16 v[46:49], v[126:129], v[206:209], v[46:49]
	v_mfma_f32_16x16x32_bf16 v[42:45], v[176:179], v[206:209], v[42:45]
	v_mfma_f32_16x16x32_bf16 v[38:41], v[126:129], v[230:233], v[38:41]
	v_mfma_f32_16x16x32_bf16 v[34:37], v[176:179], v[230:233], v[34:37]
	s_barrier
	ds_read_b128 v[186:189], v185 offset:16384
	s_add_i32 m0, s30, 0x10000
	ds_read_b128 v[190:193], v185 offset:17408
	global_load_lds_dwordx4 v16, s[8:9]
	s_add_i32 m0, s30, 0x12000
	s_add_u32 s48, s8, 0x20000
	s_addc_u32 s49, s9, 0
	ds_read_b128 v[194:197], v185 offset:18432
	global_load_lds_dwordx4 v158, s[8:9]
	s_add_i32 m0, s30, 0x14000
	ds_read_b128 v[198:201], v185 offset:19456
	global_load_lds_dwordx4 v16, s[48:49]
	s_add_i32 m0, s30, 0x16000
	ds_read_b128 v[202:205], v185 offset:20480
	global_load_lds_dwordx4 v158, s[48:49]
	s_mov_b32 m0, s31
	ds_read_b128 v[206:209], v185 offset:21504
	global_load_lds_dwordx4 v162, s[24:25]
	s_mov_b32 m0, s34
	ds_read_b128 v[210:213], v185 offset:22528
	global_load_lds_dwordx4 v160, s[24:25]
	ds_read_b128 v[230:233], v185 offset:23552
	s_waitcnt vmcnt(8)
	s_waitcnt lgkmcnt(0)
	s_barrier
	v_mfma_f32_16x16x32_bf16 v[110:113], v[58:61], v[186:189], v[110:113]
	v_mfma_f32_16x16x32_bf16 v[106:109], v[74:77], v[186:189], v[106:109]
	v_mfma_f32_16x16x32_bf16 v[102:105], v[58:61], v[194:197], v[102:105]
	v_mfma_f32_16x16x32_bf16 v[98:101], v[74:77], v[194:197], v[98:101]
	v_mfma_f32_16x16x32_bf16 v[94:97], v[58:61], v[202:205], v[94:97]
	v_mfma_f32_16x16x32_bf16 v[90:93], v[74:77], v[202:205], v[90:93]
	v_mfma_f32_16x16x32_bf16 v[58:61], v[58:61], v[210:213], v[82:85]
	v_mfma_f32_16x16x32_bf16 v[110:113], v[70:73], v[190:193], v[110:113]
	v_mfma_f32_16x16x32_bf16 v[106:109], v[86:89], v[190:193], v[106:109]
	v_mfma_f32_16x16x32_bf16 v[102:105], v[70:73], v[198:201], v[102:105]
	v_mfma_f32_16x16x32_bf16 v[98:101], v[86:89], v[198:201], v[98:101]
	v_mfma_f32_16x16x32_bf16 v[94:97], v[70:73], v[206:209], v[94:97]
	v_mfma_f32_16x16x32_bf16 v[90:93], v[86:89], v[206:209], v[90:93]
	v_mfma_f32_16x16x32_bf16 v[58:61], v[70:73], v[230:233], v[58:61]
	v_mfma_f32_16x16x32_bf16 v[70:73], v[74:77], v[210:213], v[78:81]
	v_mfma_f32_16x16x32_bf16 v[70:73], v[86:89], v[230:233], v[70:73]
	v_mfma_f32_16x16x32_bf16 v[30:33], v[122:125], v[186:189], v[30:33]
	v_mfma_f32_16x16x32_bf16 v[26:29], v[154:157], v[186:189], v[26:29]
	v_mfma_f32_16x16x32_bf16 v[22:25], v[122:125], v[194:197], v[22:25]
	v_mfma_f32_16x16x32_bf16 v[18:21], v[154:157], v[194:197], v[18:21]
	v_mfma_f32_16x16x32_bf16 v[12:15], v[122:125], v[202:205], v[12:15]
	v_mfma_f32_16x16x32_bf16 v[8:11], v[154:157], v[202:205], v[8:11]
	v_mfma_f32_16x16x32_bf16 v[4:7], v[122:125], v[210:213], v[4:7]
	v_mfma_f32_16x16x32_bf16 v[0:3], v[154:157], v[210:213], v[0:3]
	v_mfma_f32_16x16x32_bf16 v[30:33], v[126:129], v[190:193], v[30:33]
	v_mfma_f32_16x16x32_bf16 v[26:29], v[176:179], v[190:193], v[26:29]
	v_mfma_f32_16x16x32_bf16 v[22:25], v[126:129], v[198:201], v[22:25]
	v_mfma_f32_16x16x32_bf16 v[18:21], v[176:179], v[198:201], v[18:21]
	v_mfma_f32_16x16x32_bf16 v[12:15], v[126:129], v[206:209], v[12:15]
	v_mfma_f32_16x16x32_bf16 v[8:11], v[176:179], v[206:209], v[8:11]
	v_mfma_f32_16x16x32_bf16 v[4:7], v[126:129], v[230:233], v[4:7]
	v_mfma_f32_16x16x32_bf16 v[0:3], v[176:179], v[230:233], v[0:3]
	s_barrier
	s_add_u32 s100, s24, 0x20000
	s_addc_u32 s101, s25, 0
	v_add_u32_e32 v82, 0x18000, v184
	ds_read_b128 v[74:77], v82
	ds_read_b128 v[78:81], v82 offset:1024
	ds_read_b128 v[86:89], v82 offset:2048
	ds_read_b128 v[122:125], v82 offset:3072
	v_add_u32_e32 v82, 0x1c000, v184
	ds_read_b128 v[126:129], v82
	ds_read_b128 v[154:157], v82 offset:1024
	ds_read_b128 v[176:179], v82 offset:2048
	ds_read_b128 v[186:189], v82 offset:3072
	ds_read_b128 v[82:85], v185 offset:32768
	ds_read_b128 v[190:193], v185 offset:33792
	ds_read_b128 v[194:197], v185 offset:34816
	ds_read_b128 v[198:201], v185 offset:35840
	ds_read_b128 v[202:205], v185 offset:36864
	s_mov_b32 m0, s35
	ds_read_b128 v[206:209], v185 offset:37888
	global_load_lds_dwordx4 v162, s[100:101]
	s_mov_b32 m0, s36
	ds_read_b128 v[210:213], v185 offset:38912
	global_load_lds_dwordx4 v160, s[100:101]
	ds_read_b128 v[230:233], v185 offset:39936
	s_waitcnt vmcnt(8)
	s_waitcnt lgkmcnt(0)
	s_barrier
	v_mfma_f32_16x16x32_bf16 v[150:153], v[74:77], v[82:85], v[150:153]
	v_mfma_f32_16x16x32_bf16 v[146:149], v[86:89], v[82:85], v[146:149]
	v_mfma_f32_16x16x32_bf16 v[142:145], v[74:77], v[194:197], v[142:145]
	v_mfma_f32_16x16x32_bf16 v[138:141], v[86:89], v[194:197], v[138:141]
	v_mfma_f32_16x16x32_bf16 v[134:137], v[74:77], v[202:205], v[134:137]
	v_mfma_f32_16x16x32_bf16 v[130:133], v[86:89], v[202:205], v[130:133]
	v_mfma_f32_16x16x32_bf16 v[118:121], v[74:77], v[210:213], v[118:121]
	v_mfma_f32_16x16x32_bf16 v[114:117], v[86:89], v[210:213], v[114:117]
	v_mfma_f32_16x16x32_bf16 v[150:153], v[78:81], v[190:193], v[150:153]
	v_mfma_f32_16x16x32_bf16 v[146:149], v[122:125], v[190:193], v[146:149]
	v_mfma_f32_16x16x32_bf16 v[142:145], v[78:81], v[198:201], v[142:145]
	v_mfma_f32_16x16x32_bf16 v[138:141], v[122:125], v[198:201], v[138:141]
	v_mfma_f32_16x16x32_bf16 v[134:137], v[78:81], v[206:209], v[134:137]
	v_mfma_f32_16x16x32_bf16 v[130:133], v[122:125], v[206:209], v[130:133]
	v_mfma_f32_16x16x32_bf16 v[118:121], v[78:81], v[230:233], v[118:121]
	v_mfma_f32_16x16x32_bf16 v[114:117], v[122:125], v[230:233], v[114:117]
	v_mfma_f32_16x16x32_bf16 v[66:69], v[126:129], v[82:85], v[66:69]
	v_mfma_f32_16x16x32_bf16 v[62:65], v[176:179], v[82:85], v[62:65]
	v_mfma_f32_16x16x32_bf16 v[54:57], v[126:129], v[194:197], v[54:57]
	v_mfma_f32_16x16x32_bf16 v[50:53], v[176:179], v[194:197], v[50:53]
	v_mfma_f32_16x16x32_bf16 v[46:49], v[126:129], v[202:205], v[46:49]
	v_mfma_f32_16x16x32_bf16 v[42:45], v[176:179], v[202:205], v[42:45]
	v_mfma_f32_16x16x32_bf16 v[38:41], v[126:129], v[210:213], v[38:41]
	v_mfma_f32_16x16x32_bf16 v[34:37], v[176:179], v[210:213], v[34:37]
	v_mfma_f32_16x16x32_bf16 v[66:69], v[154:157], v[190:193], v[66:69]
	v_mfma_f32_16x16x32_bf16 v[62:65], v[186:189], v[190:193], v[62:65]
	v_mfma_f32_16x16x32_bf16 v[54:57], v[154:157], v[198:201], v[54:57]
	v_mfma_f32_16x16x32_bf16 v[50:53], v[186:189], v[198:201], v[50:53]
	v_mfma_f32_16x16x32_bf16 v[46:49], v[154:157], v[206:209], v[46:49]
	v_mfma_f32_16x16x32_bf16 v[42:45], v[186:189], v[206:209], v[42:45]
	v_mfma_f32_16x16x32_bf16 v[38:41], v[154:157], v[230:233], v[38:41]
	v_mfma_f32_16x16x32_bf16 v[34:37], v[186:189], v[230:233], v[34:37]
	s_barrier
	ds_read_b128 v[190:193], v185 offset:49152
	s_add_i32 m0, s30, 0x17f80
	ds_read_b128 v[194:197], v185 offset:50176
	global_load_lds_dwordx4 v16, s[8:9] offset:128
	s_add_i32 m0, s30, 0x19f80
	ds_read_b128 v[198:201], v185 offset:51200
	global_load_lds_dwordx4 v158, s[8:9] offset:128
	s_add_i32 m0, s30, 0x1bf80
	ds_read_b128 v[202:205], v185 offset:52224
	global_load_lds_dwordx4 v16, s[48:49] offset:128
	s_add_i32 m0, s30, 0x1df80
	ds_read_b128 v[206:209], v185 offset:53248
	global_load_lds_dwordx4 v158, s[48:49] offset:128
	s_add_i32 m0, s38, 0xffffff80
	ds_read_b128 v[210:213], v185 offset:54272
	global_load_lds_dwordx4 v162, s[24:25] offset:128
	s_add_i32 m0, s39, 0xffffff80
	ds_read_b128 v[230:233], v185 offset:55296
	global_load_lds_dwordx4 v160, s[24:25] offset:128
	ds_read_b128 v[234:237], v185 offset:56320
	s_waitcnt vmcnt(8)
	s_waitcnt lgkmcnt(0)
	s_barrier
	v_mfma_f32_16x16x32_bf16 v[82:85], v[74:77], v[190:193], v[110:113]
	v_mfma_f32_16x16x32_bf16 v[110:113], v[78:81], v[194:197], v[82:85]
	v_mfma_f32_16x16x32_bf16 v[82:85], v[86:89], v[190:193], v[106:109]
	v_mfma_f32_16x16x32_bf16 v[106:109], v[122:125], v[194:197], v[82:85]
	v_mfma_f32_16x16x32_bf16 v[82:85], v[74:77], v[198:201], v[102:105]
	v_mfma_f32_16x16x32_bf16 v[102:105], v[78:81], v[202:205], v[82:85]
	v_mfma_f32_16x16x32_bf16 v[82:85], v[86:89], v[198:201], v[98:101]
	v_mfma_f32_16x16x32_bf16 v[98:101], v[122:125], v[202:205], v[82:85]
	v_mfma_f32_16x16x32_bf16 v[82:85], v[74:77], v[206:209], v[94:97]
	v_mfma_f32_16x16x32_bf16 v[94:97], v[78:81], v[210:213], v[82:85]
	v_mfma_f32_16x16x32_bf16 v[82:85], v[86:89], v[206:209], v[90:93]
	v_mfma_f32_16x16x32_bf16 v[58:61], v[74:77], v[230:233], v[58:61]
	v_mfma_f32_16x16x32_bf16 v[90:93], v[122:125], v[210:213], v[82:85]
	v_mfma_f32_16x16x32_bf16 v[82:85], v[78:81], v[234:237], v[58:61]
	v_mfma_f32_16x16x32_bf16 v[58:61], v[86:89], v[230:233], v[70:73]
	v_mfma_f32_16x16x32_bf16 v[78:81], v[122:125], v[234:237], v[58:61]
	v_mfma_f32_16x16x32_bf16 v[30:33], v[126:129], v[190:193], v[30:33]
	v_mfma_f32_16x16x32_bf16 v[26:29], v[176:179], v[190:193], v[26:29]
	v_mfma_f32_16x16x32_bf16 v[22:25], v[126:129], v[198:201], v[22:25]
	v_mfma_f32_16x16x32_bf16 v[18:21], v[176:179], v[198:201], v[18:21]
	v_mfma_f32_16x16x32_bf16 v[12:15], v[126:129], v[206:209], v[12:15]
	v_mfma_f32_16x16x32_bf16 v[8:11], v[176:179], v[206:209], v[8:11]
	v_mfma_f32_16x16x32_bf16 v[4:7], v[126:129], v[230:233], v[4:7]
	v_mfma_f32_16x16x32_bf16 v[0:3], v[176:179], v[230:233], v[0:3]
	v_mfma_f32_16x16x32_bf16 v[30:33], v[154:157], v[194:197], v[30:33]
	v_mfma_f32_16x16x32_bf16 v[26:29], v[186:189], v[194:197], v[26:29]
	v_mfma_f32_16x16x32_bf16 v[22:25], v[154:157], v[202:205], v[22:25]
	v_mfma_f32_16x16x32_bf16 v[18:21], v[186:189], v[202:205], v[18:21]
	v_mfma_f32_16x16x32_bf16 v[12:15], v[154:157], v[210:213], v[12:15]
	v_mfma_f32_16x16x32_bf16 v[8:11], v[186:189], v[210:213], v[8:11]
	v_mfma_f32_16x16x32_bf16 v[4:7], v[154:157], v[234:237], v[4:7]
	v_mfma_f32_16x16x32_bf16 v[0:3], v[186:189], v[234:237], v[0:3]
	s_barrier
	s_add_i32 s46, s46, 2
	s_add_u32 s6, s6, 0x100
	s_addc_u32 s7, s7, 0
	s_add_u32 s44, s44, 0x100
	s_addc_u32 s45, s45, 0
	s_cmp_gt_u32 s46, 5
	s_cbranch_scc0 .LBB0_552
	s_and_b64 vcc, exec, s[14:15]
	s_cbranch_vccz .LBB0_555
	s_barrier

.LBB0_1018:
	s_add_u32 s26, s24, 0xfff80080
	s_addc_u32 s27, s25, -1
	s_cmp_eq_u32 s62, 28
	s_cselect_b32 s29, s19, s27
	s_cselect_b32 s28, s31, s26
	s_cselect_b32 s27, s17, s61
	s_cselect_b32 s26, s55, s60
	v_add_u32_e32 v16, 0x10000, v166
	ds_read_b128 v[144:147], v16
	ds_read_b128 v[148:151], v16 offset:1024
	ds_read_b128 v[152:155], v16 offset:2048
	ds_read_b128 v[156:159], v16 offset:3072
	v_add_u32_e32 v16, 0x14000, v166
	ds_read_b128 v[160:163], v16
	ds_read_b128 v[176:179], v16 offset:1024
	ds_read_b128 v[180:183], v16 offset:2048
	ds_read_b128 v[184:187], v16 offset:3072
	ds_read_b128 v[188:191], v167
	ds_read_b128 v[192:195], v167 offset:1024
	ds_read_b128 v[196:199], v167 offset:2048
	ds_read_b128 v[200:203], v167 offset:3072
	ds_read_b128 v[204:207], v167 offset:4096
	s_add_i32 m0, s39, 0xc000
	ds_read_b128 v[208:211], v167 offset:5120
	global_load_lds_dwordx4 v140, s[24:25]
	s_add_i32 m0, s39, 0xe000
	ds_read_b128 v[212:215], v167 offset:6144
	global_load_lds_dwordx4 v142, s[24:25]
	ds_read_b128 v[230:233], v167 offset:7168
	s_waitcnt vmcnt(8)
	s_waitcnt lgkmcnt(0)
	s_barrier
	v_mfma_f32_16x16x32_bf16 v[66:69], v[144:147], v[188:191], v[66:69]
	v_mfma_f32_16x16x32_bf16 v[62:65], v[152:155], v[188:191], v[62:65]
	v_mfma_f32_16x16x32_bf16 v[58:61], v[144:147], v[196:199], v[58:61]
	v_mfma_f32_16x16x32_bf16 v[54:57], v[152:155], v[196:199], v[54:57]
	v_mfma_f32_16x16x32_bf16 v[46:49], v[144:147], v[204:207], v[46:49]
	v_mfma_f32_16x16x32_bf16 v[42:45], v[152:155], v[204:207], v[42:45]
	v_mfma_f32_16x16x32_bf16 v[38:41], v[144:147], v[212:215], v[38:41]
	v_mfma_f32_16x16x32_bf16 v[34:37], v[152:155], v[212:215], v[34:37]
	v_mfma_f32_16x16x32_bf16 v[66:69], v[148:151], v[192:195], v[66:69]
	v_mfma_f32_16x16x32_bf16 v[62:65], v[156:159], v[192:195], v[62:65]
	v_mfma_f32_16x16x32_bf16 v[58:61], v[148:151], v[200:203], v[58:61]
	v_mfma_f32_16x16x32_bf16 v[54:57], v[156:159], v[200:203], v[54:57]
	v_mfma_f32_16x16x32_bf16 v[46:49], v[148:151], v[208:211], v[46:49]
	v_mfma_f32_16x16x32_bf16 v[42:45], v[156:159], v[208:211], v[42:45]
	v_mfma_f32_16x16x32_bf16 v[38:41], v[148:151], v[230:233], v[38:41]
	v_mfma_f32_16x16x32_bf16 v[34:37], v[156:159], v[230:233], v[34:37]
	v_mfma_f32_16x16x32_bf16 v[126:129], v[160:163], v[188:191], v[126:129]
	v_mfma_f32_16x16x32_bf16 v[122:125], v[180:183], v[188:191], v[122:125]
	v_mfma_f32_16x16x32_bf16 v[118:121], v[160:163], v[196:199], v[118:121]
	v_mfma_f32_16x16x32_bf16 v[114:117], v[180:183], v[196:199], v[114:117]
	v_mfma_f32_16x16x32_bf16 v[110:113], v[160:163], v[204:207], v[110:113]
	v_mfma_f32_16x16x32_bf16 v[106:109], v[180:183], v[204:207], v[106:109]
	v_mfma_f32_16x16x32_bf16 v[102:105], v[160:163], v[212:215], v[102:105]
	v_mfma_f32_16x16x32_bf16 v[98:101], v[180:183], v[212:215], v[98:101]
	v_mfma_f32_16x16x32_bf16 v[126:129], v[176:179], v[192:195], v[126:129]
	v_mfma_f32_16x16x32_bf16 v[122:125], v[184:187], v[192:195], v[122:125]
	v_mfma_f32_16x16x32_bf16 v[118:121], v[176:179], v[200:203], v[118:121]
	v_mfma_f32_16x16x32_bf16 v[114:117], v[184:187], v[200:203], v[114:117]
	v_mfma_f32_16x16x32_bf16 v[110:113], v[176:179], v[208:211], v[110:113]
	v_mfma_f32_16x16x32_bf16 v[106:109], v[184:187], v[208:211], v[106:109]
	v_mfma_f32_16x16x32_bf16 v[102:105], v[176:179], v[230:233], v[102:105]
	v_mfma_f32_16x16x32_bf16 v[98:101], v[184:187], v[230:233], v[98:101]
	s_barrier
	ds_read_b128 v[188:191], v167 offset:16384
	s_add_i32 m0, s38, 0x10000
	ds_read_b128 v[192:195], v167 offset:17408
	global_load_lds_dwordx4 v132, s[26:27]
	s_add_i32 m0, s38, 0x12000
	s_add_u32 s64, s26, 0x80000
	s_addc_u32 s65, s27, 0
	ds_read_b128 v[196:199], v167 offset:18432
	global_load_lds_dwordx4 v136, s[26:27]
	s_add_i32 m0, s38, 0x14000
	ds_read_b128 v[200:203], v167 offset:19456
	global_load_lds_dwordx4 v132, s[64:65]
	s_add_i32 m0, s38, 0x16000
	ds_read_b128 v[204:207], v167 offset:20480
	global_load_lds_dwordx4 v136, s[64:65]
	s_mov_b32 m0, s39
	ds_read_b128 v[208:211], v167 offset:21504
	global_load_lds_dwordx4 v130, s[28:29]
	s_mov_b32 m0, s40
	ds_read_b128 v[212:215], v167 offset:22528
	global_load_lds_dwordx4 v134, s[28:29]
	ds_read_b128 v[230:233], v167 offset:23552
	s_waitcnt vmcnt(8)
	s_waitcnt lgkmcnt(0)
	s_barrier
	v_mfma_f32_16x16x32_bf16 v[30:33], v[144:147], v[188:191], v[30:33]
	v_mfma_f32_16x16x32_bf16 v[26:29], v[152:155], v[188:191], v[26:29]
	v_mfma_f32_16x16x32_bf16 v[22:25], v[144:147], v[196:199], v[22:25]
	v_mfma_f32_16x16x32_bf16 v[18:21], v[152:155], v[196:199], v[18:21]
	v_mfma_f32_16x16x32_bf16 v[12:15], v[144:147], v[204:207], v[12:15]
	v_mfma_f32_16x16x32_bf16 v[8:11], v[152:155], v[204:207], v[8:11]
	v_mfma_f32_16x16x32_bf16 v[4:7], v[144:147], v[212:215], v[4:7]
	v_mfma_f32_16x16x32_bf16 v[0:3], v[152:155], v[212:215], v[0:3]
	v_mfma_f32_16x16x32_bf16 v[30:33], v[148:151], v[192:195], v[30:33]
	v_mfma_f32_16x16x32_bf16 v[26:29], v[156:159], v[192:195], v[26:29]
	v_mfma_f32_16x16x32_bf16 v[22:25], v[148:151], v[200:203], v[22:25]
	v_mfma_f32_16x16x32_bf16 v[18:21], v[156:159], v[200:203], v[18:21]
	v_mfma_f32_16x16x32_bf16 v[12:15], v[148:151], v[208:211], v[12:15]
	v_mfma_f32_16x16x32_bf16 v[8:11], v[156:159], v[208:211], v[8:11]
	v_mfma_f32_16x16x32_bf16 v[4:7], v[148:151], v[230:233], v[4:7]
	v_mfma_f32_16x16x32_bf16 v[0:3], v[156:159], v[230:233], v[0:3]
	v_mfma_f32_16x16x32_bf16 v[94:97], v[160:163], v[188:191], v[94:97]
	v_mfma_f32_16x16x32_bf16 v[90:93], v[180:183], v[188:191], v[90:93]
	v_mfma_f32_16x16x32_bf16 v[86:89], v[160:163], v[196:199], v[86:89]
	v_mfma_f32_16x16x32_bf16 v[82:85], v[180:183], v[196:199], v[82:85]
	v_mfma_f32_16x16x32_bf16 v[78:81], v[160:163], v[204:207], v[78:81]
	v_mfma_f32_16x16x32_bf16 v[74:77], v[180:183], v[204:207], v[74:77]
	v_mfma_f32_16x16x32_bf16 v[70:73], v[160:163], v[212:215], v[70:73]
	v_mfma_f32_16x16x32_bf16 v[50:53], v[180:183], v[212:215], v[50:53]
	v_mfma_f32_16x16x32_bf16 v[94:97], v[176:179], v[192:195], v[94:97]
	v_mfma_f32_16x16x32_bf16 v[90:93], v[184:187], v[192:195], v[90:93]
	v_mfma_f32_16x16x32_bf16 v[86:89], v[176:179], v[200:203], v[86:89]
	v_mfma_f32_16x16x32_bf16 v[82:85], v[184:187], v[200:203], v[82:85]
	v_mfma_f32_16x16x32_bf16 v[78:81], v[176:179], v[208:211], v[78:81]
	v_mfma_f32_16x16x32_bf16 v[74:77], v[184:187], v[208:211], v[74:77]
	v_mfma_f32_16x16x32_bf16 v[70:73], v[176:179], v[230:233], v[70:73]
	v_mfma_f32_16x16x32_bf16 v[50:53], v[184:187], v[230:233], v[50:53]
	s_barrier
	s_add_u32 s100, s28, 0x80000
	s_addc_u32 s101, s29, 0
	v_add_u32_e32 v16, 0x18000, v166
	ds_read_b128 v[144:147], v16
	ds_read_b128 v[148:151], v16 offset:1024
	ds_read_b128 v[152:155], v16 offset:2048
	ds_read_b128 v[156:159], v16 offset:3072
	v_add_u32_e32 v16, 0x1c000, v166
	ds_read_b128 v[160:163], v16
	ds_read_b128 v[176:179], v16 offset:1024
	ds_read_b128 v[180:183], v16 offset:2048
	ds_read_b128 v[184:187], v16 offset:3072
	ds_read_b128 v[188:191], v167 offset:32768
	ds_read_b128 v[192:195], v167 offset:33792
	ds_read_b128 v[196:199], v167 offset:34816
	ds_read_b128 v[200:203], v167 offset:35840
	ds_read_b128 v[204:207], v167 offset:36864
	s_mov_b32 m0, s41
	ds_read_b128 v[208:211], v167 offset:37888
	global_load_lds_dwordx4 v130, s[100:101]
	s_mov_b32 m0, s42
	ds_read_b128 v[212:215], v167 offset:38912
	global_load_lds_dwordx4 v134, s[100:101]
	ds_read_b128 v[230:233], v167 offset:39936
	s_waitcnt vmcnt(8)
	s_waitcnt lgkmcnt(0)
	s_barrier
	v_mfma_f32_16x16x32_bf16 v[66:69], v[144:147], v[188:191], v[66:69]
	v_mfma_f32_16x16x32_bf16 v[62:65], v[152:155], v[188:191], v[62:65]
	v_mfma_f32_16x16x32_bf16 v[58:61], v[144:147], v[196:199], v[58:61]
	v_mfma_f32_16x16x32_bf16 v[54:57], v[152:155], v[196:199], v[54:57]
	v_mfma_f32_16x16x32_bf16 v[46:49], v[144:147], v[204:207], v[46:49]
	v_mfma_f32_16x16x32_bf16 v[42:45], v[152:155], v[204:207], v[42:45]
	v_mfma_f32_16x16x32_bf16 v[38:41], v[144:147], v[212:215], v[38:41]
	v_mfma_f32_16x16x32_bf16 v[34:37], v[152:155], v[212:215], v[34:37]
	v_mfma_f32_16x16x32_bf16 v[66:69], v[148:151], v[192:195], v[66:69]
	v_mfma_f32_16x16x32_bf16 v[62:65], v[156:159], v[192:195], v[62:65]
	v_mfma_f32_16x16x32_bf16 v[58:61], v[148:151], v[200:203], v[58:61]
	v_mfma_f32_16x16x32_bf16 v[54:57], v[156:159], v[200:203], v[54:57]
	v_mfma_f32_16x16x32_bf16 v[46:49], v[148:151], v[208:211], v[46:49]
	v_mfma_f32_16x16x32_bf16 v[42:45], v[156:159], v[208:211], v[42:45]
	v_mfma_f32_16x16x32_bf16 v[38:41], v[148:151], v[230:233], v[38:41]
	v_mfma_f32_16x16x32_bf16 v[34:37], v[156:159], v[230:233], v[34:37]
	v_mfma_f32_16x16x32_bf16 v[126:129], v[160:163], v[188:191], v[126:129]
	v_mfma_f32_16x16x32_bf16 v[122:125], v[180:183], v[188:191], v[122:125]
	v_mfma_f32_16x16x32_bf16 v[118:121], v[160:163], v[196:199], v[118:121]
	v_mfma_f32_16x16x32_bf16 v[114:117], v[180:183], v[196:199], v[114:117]
	v_mfma_f32_16x16x32_bf16 v[110:113], v[160:163], v[204:207], v[110:113]
	v_mfma_f32_16x16x32_bf16 v[106:109], v[180:183], v[204:207], v[106:109]
	v_mfma_f32_16x16x32_bf16 v[102:105], v[160:163], v[212:215], v[102:105]
	v_mfma_f32_16x16x32_bf16 v[98:101], v[180:183], v[212:215], v[98:101]
	v_mfma_f32_16x16x32_bf16 v[126:129], v[176:179], v[192:195], v[126:129]
	v_mfma_f32_16x16x32_bf16 v[122:125], v[184:187], v[192:195], v[122:125]
	v_mfma_f32_16x16x32_bf16 v[118:121], v[176:179], v[200:203], v[118:121]
	v_mfma_f32_16x16x32_bf16 v[114:117], v[184:187], v[200:203], v[114:117]
	v_mfma_f32_16x16x32_bf16 v[110:113], v[176:179], v[208:211], v[110:113]
	v_mfma_f32_16x16x32_bf16 v[106:109], v[184:187], v[208:211], v[106:109]
	v_mfma_f32_16x16x32_bf16 v[102:105], v[176:179], v[230:233], v[102:105]
	v_mfma_f32_16x16x32_bf16 v[98:101], v[184:187], v[230:233], v[98:101]
	s_barrier
	ds_read_b128 v[188:191], v167 offset:49152
	s_add_i32 m0, s38, 0x17f80
	ds_read_b128 v[192:195], v167 offset:50176
	global_load_lds_dwordx4 v132, s[26:27] offset:128
	s_add_i32 m0, s38, 0x19f80
	ds_read_b128 v[196:199], v167 offset:51200
	global_load_lds_dwordx4 v136, s[26:27] offset:128
	s_add_i32 m0, s38, 0x1bf80
	ds_read_b128 v[200:203], v167 offset:52224
	global_load_lds_dwordx4 v132, s[64:65] offset:128
	s_add_i32 m0, s38, 0x1df80
	ds_read_b128 v[204:207], v167 offset:53248
	global_load_lds_dwordx4 v136, s[64:65] offset:128
	s_add_i32 m0, s46, 0xffffff80
	ds_read_b128 v[208:211], v167 offset:54272
	global_load_lds_dwordx4 v130, s[28:29] offset:128
	s_add_i32 m0, s47, 0xffffff80
	ds_read_b128 v[212:215], v167 offset:55296
	global_load_lds_dwordx4 v134, s[28:29] offset:128
	ds_read_b128 v[230:233], v167 offset:56320
	s_waitcnt vmcnt(8)
	s_waitcnt lgkmcnt(0)
	s_barrier
	v_mfma_f32_16x16x32_bf16 v[30:33], v[144:147], v[188:191], v[30:33]
	v_mfma_f32_16x16x32_bf16 v[26:29], v[152:155], v[188:191], v[26:29]
	v_mfma_f32_16x16x32_bf16 v[22:25], v[144:147], v[196:199], v[22:25]
	v_mfma_f32_16x16x32_bf16 v[18:21], v[152:155], v[196:199], v[18:21]
	v_mfma_f32_16x16x32_bf16 v[12:15], v[144:147], v[204:207], v[12:15]
	v_mfma_f32_16x16x32_bf16 v[8:11], v[152:155], v[204:207], v[8:11]
	v_mfma_f32_16x16x32_bf16 v[4:7], v[144:147], v[212:215], v[4:7]
	v_mfma_f32_16x16x32_bf16 v[0:3], v[152:155], v[212:215], v[0:3]
	v_mfma_f32_16x16x32_bf16 v[30:33], v[148:151], v[192:195], v[30:33]
	v_mfma_f32_16x16x32_bf16 v[26:29], v[156:159], v[192:195], v[26:29]
	v_mfma_f32_16x16x32_bf16 v[22:25], v[148:151], v[200:203], v[22:25]
	v_mfma_f32_16x16x32_bf16 v[18:21], v[156:159], v[200:203], v[18:21]
	v_mfma_f32_16x16x32_bf16 v[12:15], v[148:151], v[208:211], v[12:15]
	v_mfma_f32_16x16x32_bf16 v[8:11], v[156:159], v[208:211], v[8:11]
	v_mfma_f32_16x16x32_bf16 v[4:7], v[148:151], v[230:233], v[4:7]
	v_mfma_f32_16x16x32_bf16 v[0:3], v[156:159], v[230:233], v[0:3]
	v_mfma_f32_16x16x32_bf16 v[94:97], v[160:163], v[188:191], v[94:97]
	v_mfma_f32_16x16x32_bf16 v[90:93], v[180:183], v[188:191], v[90:93]
	v_mfma_f32_16x16x32_bf16 v[86:89], v[160:163], v[196:199], v[86:89]
	v_mfma_f32_16x16x32_bf16 v[82:85], v[180:183], v[196:199], v[82:85]
	v_mfma_f32_16x16x32_bf16 v[78:81], v[160:163], v[204:207], v[78:81]
	v_mfma_f32_16x16x32_bf16 v[74:77], v[180:183], v[204:207], v[74:77]
	v_mfma_f32_16x16x32_bf16 v[70:73], v[160:163], v[212:215], v[70:73]
	v_mfma_f32_16x16x32_bf16 v[50:53], v[180:183], v[212:215], v[50:53]
	v_mfma_f32_16x16x32_bf16 v[94:97], v[176:179], v[192:195], v[94:97]
	v_mfma_f32_16x16x32_bf16 v[90:93], v[184:187], v[192:195], v[90:93]
	v_mfma_f32_16x16x32_bf16 v[86:89], v[176:179], v[200:203], v[86:89]
	v_mfma_f32_16x16x32_bf16 v[82:85], v[184:187], v[200:203], v[82:85]
	v_mfma_f32_16x16x32_bf16 v[78:81], v[176:179], v[208:211], v[78:81]
	v_mfma_f32_16x16x32_bf16 v[74:77], v[184:187], v[208:211], v[74:77]
	v_mfma_f32_16x16x32_bf16 v[70:73], v[176:179], v[230:233], v[70:73]
	v_mfma_f32_16x16x32_bf16 v[50:53], v[184:187], v[230:233], v[50:53]
	s_barrier
	s_add_i32 s62, s62, 2
	s_add_u32 s24, s24, 0x100
	s_addc_u32 s25, s25, 0
	s_add_u32 s60, s60, 0x100
	s_addc_u32 s61, s61, 0
	s_cmp_gt_u32 s62, 29
	s_cbranch_scc0 .LBB0_1018
	s_and_b64 vcc, exec, s[8:9]
	s_cbranch_vccz .LBB0_1021
	s_barrier
